# e41: e40 + split P0->P1 grid barrier: arrive after P0, run the P0-independent part of P1 (S5 tables / weight-transpose items, entered first), wait only in front of the fold GEMM and the rmsnorm rows
# speedup vs baseline: 1.0154x; 1.0057x over previous
; __device__ __forceinline__ unsigned xb_ld(unsigned* p)              { return __hip_atomic_load(p, __ATOMIC_RELAXED, __HIP_MEMORY_SCOPE_AGENT); }
; __device__ __forceinline__ unsigned xb_add(unsigned* p, unsigned v) { return __hip_atomic_fetch_add(p, v, __ATOMIC_RELAXED, __HIP_MEMORY_SCOPE_AGENT); }
; #define XB_SPIN(cond, bar) do { unsigned _sp = 0; while (cond) { __builtin_amdgcn_s_sleep(1); \
;     if ((++_sp & 255u) == 0u) { if (xb_ld(&(bar)[XB_TMO])) break; if (_sp > XB_SPIN_CAP) { atomicAdd(&(bar)[XB_TMO], 1u); break; } } } } while (0)
; __device__ __forceinline__ void xcd_barrier(const XcdBarrier& b) {
;     asm volatile("s_waitcnt vmcnt(0)" ::: "memory");
;     __syncthreads();
;     if (threadIdx.x == 0) {
;         unsigned* bar = b.bar;
;         __builtin_amdgcn_s_waitcnt(0);
;         unsigned nloc = b.st[0], nx = b.st[1];
;         if (nloc == 0u) { xcd_barrier_complete(bar, b.x, nloc, nx); b.st[0] = nloc; b.st[1] = nx; }
;         const unsigned old = xb_add(&bar[XB_XSUB(b.x)], 1u);
;         const unsigned gen = old / nloc;
;         if (old + 1u == (gen + 1u) * nloc) {
;             __builtin_amdgcn_fence(__ATOMIC_RELEASE, "agent");
;             asm volatile("s_waitcnt vmcnt(0)" ::: "memory");
;             const unsigned og = xb_add(&bar[XB_TOP], 1u);
;             const unsigned tg = og / nx;
;             if (og + 1u == (tg + 1u) * nx) xb_add(&bar[XB_TOPGEN], 1u);
;             else XB_SPIN(xb_ld(&bar[XB_TOPGEN]) == tg, bar);
;             __builtin_amdgcn_fence(__ATOMIC_ACQUIRE, "agent");
;             xb_add(&bar[XB_XGEN(b.x)], 1u);
;             asm volatile("s_waitcnt vmcnt(0)" ::: "memory");
;         } else {
;             XB_SPIN(xb_ld(&bar[XB_XGEN(b.x)]) == gen, bar);
.LBB0_97:
	s_or_b64 exec, exec, s[10:11]
	v_cvt_f32_u32_e32 v5, v3
	s_waitcnt vmcnt(0)
	v_readfirstlane_b32 s0, v4
	v_sub_u32_e32 v4, 0, v3
	v_rcp_iflag_f32_e32 v5, v5
	v_add_u32_e32 v6, s0, v2
	v_mul_f32_e32 v5, 0x4f7ffffe, v5
	v_cvt_u32_f32_e32 v5, v5
	v_mul_lo_u32 v2, v4, v5
	v_mul_hi_u32 v2, v5, v2
	v_add_u32_e32 v2, v5, v2
	v_mul_hi_u32 v2, v6, v2
	v_mul_lo_u32 v4, v2, v3
	v_sub_u32_e32 v4, v6, v4
	v_add_u32_e32 v5, 1, v2
	v_cmp_ge_u32_e32 vcc, v4, v3
	s_nop 1
	v_cndmask_b32_e32 v2, v2, v5, vcc
	v_sub_u32_e32 v5, v4, v3
	v_cndmask_b32_e32 v4, v4, v5, vcc
	v_add_u32_e32 v5, 1, v2
	v_cmp_ge_u32_e32 vcc, v4, v3
	v_add_u32_e32 v4, 1, v6
	s_nop 0
	v_cndmask_b32_e32 v2, v2, v5, vcc
	v_mul_lo_u32 v5, v3, v2
	v_add_u32_e32 v3, v5, v3
	v_cmp_ne_u32_e32 vcc, v4, v3
	s_and_saveexec_b64 s[0:1], vcc
	s_xor_b64 s[8:9], exec, s[0:1]
	s_cbranch_execz .LBB0_111
	s_waitcnt lgkmcnt(0)
	buffer_inv sc1
	s_mov_b64 s[10:11], exec

; __device__ __forceinline__ unsigned xb_ld(unsigned* p)              { return __hip_atomic_load(p, __ATOMIC_RELAXED, __HIP_MEMORY_SCOPE_AGENT); }
; __device__ __forceinline__ unsigned xb_add(unsigned* p, unsigned v) { return __hip_atomic_fetch_add(p, v, __ATOMIC_RELAXED, __HIP_MEMORY_SCOPE_AGENT); }
; #define XB_SPIN(cond, bar) do { unsigned _sp = 0; while (cond) { __builtin_amdgcn_s_sleep(1); \
;     if ((++_sp & 255u) == 0u) { if (xb_ld(&(bar)[XB_TMO])) break; if (_sp > XB_SPIN_CAP) { atomicAdd(&(bar)[XB_TMO], 1u); break; } } } } while (0)
; __device__ __forceinline__ void xcd_barrier(const XcdBarrier& b) {
;     ...
;         const unsigned old = xb_add(&bar[XB_XSUB(b.x)], 1u);
;         const unsigned gen = old / nloc;
;         if (old + 1u == (gen + 1u) * nloc) {
;             __builtin_amdgcn_fence(__ATOMIC_RELEASE, "agent");
;             asm volatile("s_waitcnt vmcnt(0)" ::: "memory");
;             const unsigned og = xb_add(&bar[XB_TOP], 1u);
;             const unsigned tg = og / nx;
;             if (og + 1u == (tg + 1u) * nx) xb_add(&bar[XB_TOPGEN], 1u);
;             else XB_SPIN(xb_ld(&bar[XB_TOPGEN]) == tg, bar);
;             __builtin_amdgcn_fence(__ATOMIC_ACQUIRE, "agent");
.LBB0_114:
	s_or_b64 exec, exec, s[10:11]
	v_cvt_f32_u32_e32 v4, v1
	s_waitcnt vmcnt(0)
	v_readfirstlane_b32 s0, v3
	s_add_u32 s10, s50, 0x3500
	s_addc_u32 s11, s51, 0
	v_rcp_iflag_f32_e32 v4, v4
	v_add_u32_e32 v2, s0, v2
	v_add_u32_e32 v5, 1, v2
	s_mov_b64 s[12:13], -1
	v_mul_f32_e32 v3, 0x4f7ffffe, v4
	v_cvt_u32_f32_e32 v3, v3
	v_sub_u32_e32 v4, 0, v1
	v_mul_lo_u32 v4, v4, v3
	v_mul_hi_u32 v4, v3, v4
	v_add_u32_e32 v3, v3, v4
	v_mul_hi_u32 v3, v2, v3
	v_mul_lo_u32 v4, v3, v1
	v_sub_u32_e32 v2, v2, v4
	v_add_u32_e32 v6, 1, v3
	v_cmp_ge_u32_e32 vcc, v2, v1
	v_sub_u32_e32 v4, v2, v1
	s_nop 0
	v_cndmask_b32_e32 v3, v3, v6, vcc
	v_cndmask_b32_e32 v2, v2, v4, vcc
	v_add_u32_e32 v4, 1, v3
	v_cmp_ge_u32_e32 vcc, v2, v1
	s_nop 1
	v_cndmask_b32_e32 v4, v3, v4, vcc
	v_mul_lo_u32 v2, v1, v4
	v_add_u32_e32 v1, v2, v1
	v_cmp_ne_u32_e32 vcc, v5, v1
	v_mov_b64_e32 v[2:3], s[10:11]
	s_and_saveexec_b64 s[8:9], vcc
	s_cbranch_execz .LBB0_126
	s_mov_b64 s[12:13], 0

; #define LAS __attribute__((address_space(3)))
; #define SUB(i, ...) do { if (PROBE_PH == phk && PROBE_SUB == (i)) { __syncthreads(); tp0 = __builtin_amdgcn_s_memrealtime(); } __VA_ARGS__ if (PROBE_PH == phk && PROBE_SUB == (i)) { asm volatile("s_waitcnt vmcnt(0)" ::: "memory"); __syncthreads(); tp1 = __builtin_amdgcn_s_memrealtime(); } } while (0)
; __global__ void __launch_bounds__(NTHREADS, 2) mk_fwd(Args a) {
;     ...
;     PHASE(1,
;         LAS float* scr = (LAS float*)lds + wave * (64 * 33);
;         SUB(0, if (vcu < 128) ssm_tables((LAS float*)lds, vcu, a.in[10], a.in[11], a.in[12], a.in[13], a.in[14], a.in[15], a.in[16], (f16*)(a.ws + WS_PG), (f16*)(a.ws + WS_QG), (f16*)(a.ws + WS_KTH)); );
;         { pg8::ListOrder S; S.init(32, 1, 8, G, vcu >= 128 && vcu < 160 ? vcu - 128 : 1 << 20);
;           EpiWp E{(f16*)(a.ws + WS_WIN)};
;           SUB(3, pg8::gemm_phase<CfgWp, EpiWp, pg8::ListOrder, true, true>(lds, (const char*)(a.ws + WS_WPOOL), (const char*)(a.ws + WS_WRAW), S, E); ); }
;         SUB(1, norm_rows(vcu * NWAVES + wave, lane, a.in[0], a.in[2], a.in[6], (const float*)(a.ws + WS_MOD), (f16*)(a.ws + WS_H)); );
;         SUB(2, if (vcu < 128) transpose_dispatch((320 + vcu) * 8 + wave, a.in[7], a.in[20], a.in[18], a.in[8], a.ws, scr, lane);
;                else { const int b2 = vcu - 128;
;                    for (int it = 448 + 3 * b2; it < 448 + 3 * b2 + 3; ++it) transpose_dispatch(it * 8 + wave, a.in[7], a.in[20], a.in[18], a.in[8], a.ws, scr, lane);
;                    if (b2 < 16) transpose_dispatch((832 + b2) * 8 + wave, a.in[7], a.in[20], a.in[18], a.in[8], a.ws, scr, lane); } );
.LBB0_132:
	s_cmp_lt_i32 s78, 2
	s_cselect_b64 s[0:1], -1, 0
	s_and_b64 s[76:77], s[0:1], s[4:5]
	s_andn2_b64 vcc, exec, s[76:77]
	s_cbranch_vccnz .LBB0_230
	s_mov_b32 s100, 0
	s_cmpk_gt_i32 s81, 0x7f
	s_cselect_b64 s[18:19], -1, 0
	s_cmpk_lt_i32 s81, 0x80
	s_cbranch_scc1 .LBB0_135
	v_and_b32_e32 v22, 15, v0
	v_lshrrev_b32_e32 v1, 1, v0
	s_mov_b32 s100, 1
	s_lshl_b32 s6, s81, 3
	s_add_i32 s6, s6, s53
	s_add_i32 s20, s81, 0xffffff80
	s_add_u32 s0, s50, 0x2000000
	s_addc_u32 s1, s51, 0
	s_add_u32 s4, s50, 0x13600000
	s_addc_u32 s5, s51, 0
	s_branch .LBB0_184

; __device__ __forceinline__ unsigned xb_ld(unsigned* p)              { return __hip_atomic_load(p, __ATOMIC_RELAXED, __HIP_MEMORY_SCOPE_AGENT); }
; #define XB_SPIN(cond, bar) do { unsigned _sp = 0; while (cond) { __builtin_amdgcn_s_sleep(1); \
;     if ((++_sp & 255u) == 0u) { if (xb_ld(&(bar)[XB_TMO])) break; if (_sp > XB_SPIN_CAP) { atomicAdd(&(bar)[XB_TMO], 1u); break; } } } } while (0)
; #define SUB(i, ...) do { if (PROBE_PH == phk && PROBE_SUB == (i)) { __syncthreads(); tp0 = __builtin_amdgcn_s_memrealtime(); } __VA_ARGS__ if (PROBE_PH == phk && PROBE_SUB == (i)) { asm volatile("s_waitcnt vmcnt(0)" ::: "memory"); __syncthreads(); tp1 = __builtin_amdgcn_s_memrealtime(); } } while (0)
; __device__ __forceinline__ void xcd_barrier(const XcdBarrier& b) {
;     ...
;             XB_SPIN(xb_ld(&bar[XB_XGEN(b.x)]) == gen, bar);
; __global__ void __launch_bounds__(NTHREADS, 2) mk_fwd(Args a) {
;     ...
;         { pg8::ListOrder S; S.init(32, 1, 8, G, vcu >= 128 && vcu < 160 ? vcu - 128 : 1 << 20);
;           EpiWp E{(f16*)(a.ws + WS_WIN)};
;           SUB(3, pg8::gemm_phase<CfgWp, EpiWp, pg8::ListOrder, true, true>(lds, (const char*)(a.ws + WS_WPOOL), (const char*)(a.ws + WS_WRAW), S, E); ); }
.LBB0_165:
	s_and_saveexec_b64 s[2:3], s[82:83]
	s_cbranch_execz .Lp1_waited
	v_mov_b32_e32 v2, 0x3500
	s_mov_b32 s0, 0
.Lp1_wait:
	global_load_dword v3, v2, s[50:51] sc1
	s_add_u32 s0, s0, 1
	s_waitcnt vmcnt(0)
	v_readfirstlane_b32 s1, v3
	s_cmp_lg_u32 s1, 0
	s_cbranch_scc1 .Lp1_polled
	s_cmp_gt_u32 s0, 0x4000
	s_cbranch_scc1 .Lp1_polled
	s_sleep 1
	s_branch .Lp1_wait

; #define PG8_STAGE_A(bufoff, gbase) PG8_STAGE(bufoff, gbase, voffA, a64)
; #define PG8_STAGE_B(bufoff, bp, hb, tz) do { if (BMODE == 1 && (tz)) PG8_STAGE(bufoff, (bp) + (hb) * 4096, voffT, t64); else PG8_STAGE(bufoff, (bp) + (hb) * bhstep, voffB, b64); } while (0)
; #define PG8_WAIT_V(n) asm volatile("s_waitcnt vmcnt(" #n ")" ::: "memory")
; #define PG8_BAR __builtin_amdgcn_s_barrier()
; #define SUB(i, ...) do { if (PROBE_PH == phk && PROBE_SUB == (i)) { __syncthreads(); tp0 = __builtin_amdgcn_s_memrealtime(); } __VA_ARGS__ if (PROBE_PH == phk && PROBE_SUB == (i)) { asm volatile("s_waitcnt vmcnt(0)" ::: "memory"); __syncthreads(); tp1 = __builtin_amdgcn_s_memrealtime(); } } while (0)
; template <class CF, class Epi, class Sched, bool ALIGN_EPI, bool SP2>
; __device__ __forceinline__ void gemm_phase(LAS unsigned char* lds, const char* gA, const char* gB, const Sched& S, const Epi& E, const char* gB2 = nullptr) {
;     ...
;     const char* cA = gA + (size_t)cur.g * CF::A_G + (size_t)cur.pm * CF::A_T; const char* cB = gB + (size_t)cur.g * CF::B_G + (size_t)cur.pn * CF::B_T;
;     const char* cT = BMODE == 1 ? gB2 + (size_t)cur.g * KTG + (size_t)cur.pn * 8192 + 14336 : nullptr;
;     PG8_STAGE_B(PG8_SB(0, 0), cB, 0, false); PG8_STAGE_B(PG8_SB(0, 1), cB, 1, false); PG8_STAGE_A(PG8_SA(0, 0), cA); PG8_STAGE_A(PG8_SA(0, 1), cA + ahstep);
;     if (wr == 1) PG8_BAR;
;     PG8_WAIT_V(2); PG8_BAR;
;     PG8_STAGE_B(PG8_SB(1, 0), cB + bkstep, 0, false); PG8_STAGE_A(PG8_SA(1, 0), cA + akstep); PG8_STAGE_B(PG8_SB(1, 1), cB + bkstep, 1, false);
;     PG8_WAIT_V(6); PG8_BAR;
; __global__ void __launch_bounds__(NTHREADS, 2) mk_fwd(Args a) {
;     ...
;         { pg8::ListOrder S; S.init(32, 1, 8, G, vcu >= 128 && vcu < 160 ? vcu - 128 : 1 << 20);
;           EpiWp E{(f16*)(a.ws + WS_WIN)};
;           SUB(3, pg8::gemm_phase<CfgWp, EpiWp, pg8::ListOrder, true, true>(lds, (const char*)(a.ws + WS_WPOOL), (const char*)(a.ws + WS_WRAW), S, E); ); }
.Lp1_waited:
	s_or_b64 exec, exec, s[2:3]
	s_waitcnt lgkmcnt(0)
	s_barrier
	s_and_b32 s0, s81, 0xffffffe0
	s_add_i32 s20, s81, 0xffffff80
	s_cmpk_eq_i32 s0, 0x80
	s_cselect_b32 s10, s20, 0x100000
	s_add_u32 s0, s50, 0x2000000
	s_addc_u32 s1, s51, 0
	s_add_u32 s4, s50, 0x13600000
	s_addc_u32 s5, s51, 0
	s_cmp_gt_i32 s10, 31
	v_readfirstlane_b32 s11, v0
	s_cbranch_scc1 .LBB0_179
	s_ashr_i32 s2, s10, 31
	s_lshr_b32 s2, s2, 29
	s_add_i32 s2, s10, s2
	s_ashr_i32 s84, s2, 3
	s_mov_b32 s65, s20
	v_writelane_b32 v254, s18, 34
	s_lshr_b32 s20, s11, 6
	s_and_b32 s2, s2, -8
	s_ashr_i32 s85, s84, 31
	v_writelane_b32 v254, s19, 35
	s_lshr_b32 s19, s11, 8
	s_lshl_b32 s33, s20, 10
	v_lshrrev_b32_e32 v2, 5, v0
	v_bfe_u32 v3, v0, 2, 2
	s_sub_i32 s86, s10, s2
	s_lshl_b64 s[2:3], s[84:85], 17
	v_and_or_b32 v2, v2, 4, v3
	v_lshrrev_b32_e32 v3, 3, v0
	v_lshrrev_b32_e32 v5, 1, v0
	s_add_u32 s88, s0, s2
	v_and_b32_e32 v4, 32, v3
	v_and_b32_e32 v5, 24, v5
	s_addc_u32 s89, s1, s3
	s_lshl_b64 s[2:3], s[84:85], 9
	v_or3_b32 v2, v2, v4, v5
	v_lshlrev_b32_e32 v4, 4, v0
	v_and_b32_e32 v5, 32, v0
	s_add_u32 s6, s4, s2
	v_bitop3_b32 v4, v4, v5, 48 bitop3:0x6c
	s_addc_u32 s7, s5, s3
	s_ashr_i32 s87, s86, 31
	v_and_or_b32 v4, v0, 64, v4
	s_lshl_b64 s[2:3], s[86:87], 19
	v_lshl_or_b32 v130, v2, 11, v4
	v_bfe_u32 v2, v0, 2, 4
	s_add_u32 s92, s6, s2
	v_and_or_b32 v2, v3, 48, v2
	s_addc_u32 s93, s7, s3
	v_mov_b32_e32 v131, 0
	s_add_i32 s87, s33, 0
	v_lshl_or_b32 v132, v2, 9, v4
	v_lshl_add_u64 v[2:3], s[92:93], 0, v[130:131]
	s_add_i32 m0, s87, 0x10000
	s_mov_b64 s[2:3], 0x20000
	global_load_lds_dwordx4 v130, s[92:93]
	v_lshl_add_u64 v[4:5], v[2:3], 0, s[2:3]
	s_add_i32 m0, s87, 0x12000
	s_mov_b64 s[6:7], 0x40000
	global_load_lds_dwordx4 v[4:5], off
	v_lshl_add_u64 v[4:5], v[2:3], 0, s[6:7]
	s_add_i32 m0, s87, 0x14000
	s_mov_b64 s[12:13], 0x60000
	global_load_lds_dwordx4 v[4:5], off
	v_lshl_add_u64 v[4:5], v[2:3], 0, s[12:13]
	s_add_i32 m0, s87, 0x16000
	v_mov_b32_e32 v133, v131
	global_load_lds_dwordx4 v[4:5], off
	v_lshl_add_u64 v[4:5], s[88:89], 0, v[132:133]
	s_mov_b32 m0, s87
	s_mov_b64 s[14:15], 0x8000
	s_add_i32 s8, s87, 0x2000
	global_load_lds_dwordx4 v132, s[88:89]
	v_lshl_add_u64 v[6:7], v[4:5], 0, s[14:15]
	s_mov_b32 m0, s8
	s_mov_b64 s[22:23], 0x10000
	s_add_i32 s9, s87, 0x4000
	global_load_lds_dwordx4 v[6:7], off
	v_lshl_add_u64 v[6:7], v[4:5], 0, s[22:23]
	s_mov_b32 m0, s9
	s_mov_b64 s[24:25], 0x18000
	s_add_i32 s18, s87, 0x6000
	global_load_lds_dwordx4 v[6:7], off
	v_lshl_add_u64 v[6:7], v[4:5], 0, s[24:25]
	s_mov_b32 m0, s18
	s_cmp_eq_u32 s19, 1
	global_load_lds_dwordx4 v[6:7], off
	v_writelane_b32 v254, s76, 36
	s_mov_b64 s[66:67], s[82:83]
	s_mov_b32 s64, s52
	s_mov_b64 s[56:57], s[78:79]
	s_mov_b32 s52, s81
	s_cselect_b64 s[26:27], -1, 0
	s_cmp_lg_u32 s19, 1
	v_writelane_b32 v254, s77, 37
	s_cbranch_scc1 .LBB0_168
	s_barrier

; #define SUB(i, ...) do { if (PROBE_PH == phk && PROBE_SUB == (i)) { __syncthreads(); tp0 = __builtin_amdgcn_s_memrealtime(); } __VA_ARGS__ if (PROBE_PH == phk && PROBE_SUB == (i)) { asm volatile("s_waitcnt vmcnt(0)" ::: "memory"); __syncthreads(); tp1 = __builtin_amdgcn_s_memrealtime(); } } while (0)
; __global__ void __launch_bounds__(NTHREADS, 2) mk_fwd(Args a) {
;     ...
;         SUB(2, if (vcu < 128) transpose_dispatch((320 + vcu) * 8 + wave, a.in[7], a.in[20], a.in[18], a.in[8], a.ws, scr, lane);
;                else { const int b2 = vcu - 128;
;                    for (int it = 448 + 3 * b2; it < 448 + 3 * b2 + 3; ++it) transpose_dispatch(it * 8 + wave, a.in[7], a.in[20], a.in[18], a.in[8], a.ws, scr, lane);
;                    if (b2 < 16) transpose_dispatch((832 + b2) * 8 + wave, a.in[7], a.in[20], a.in[18], a.in[8], a.ws, scr, lane); } );
.LBB0_184:
	s_cmp_eq_u32 s100, 2
	s_cbranch_scc1 .LBB0_230
	s_mov_b32 s99, 0
	s_mul_i32 s2, s53, 0x2100
	s_mov_b32 s13, 0
	s_add_i32 s28, s2, 0
	s_mov_b64 s[2:3], -1
	s_and_b64 vcc, exec, s[18:19]
	s_cbranch_vccz .LBB0_230

; #define LAS __attribute__((address_space(3)))
; #define SUB(i, ...) do { if (PROBE_PH == phk && PROBE_SUB == (i)) { __syncthreads(); tp0 = __builtin_amdgcn_s_memrealtime(); } __VA_ARGS__ if (PROBE_PH == phk && PROBE_SUB == (i)) { asm volatile("s_waitcnt vmcnt(0)" ::: "memory"); __syncthreads(); tp1 = __builtin_amdgcn_s_memrealtime(); } } while (0)
; __global__ void __launch_bounds__(NTHREADS, 2) mk_fwd(Args a) {
;     ...
;     PHASE(1,
;         LAS float* scr = (LAS float*)lds + wave * (64 * 33);
;         SUB(0, if (vcu < 128) ssm_tables((LAS float*)lds, vcu, a.in[10], a.in[11], a.in[12], a.in[13], a.in[14], a.in[15], a.in[16], (f16*)(a.ws + WS_PG), (f16*)(a.ws + WS_QG), (f16*)(a.ws + WS_KTH)); );
;         { pg8::ListOrder S; S.init(32, 1, 8, G, vcu >= 128 && vcu < 160 ? vcu - 128 : 1 << 20);
;           EpiWp E{(f16*)(a.ws + WS_WIN)};
;           SUB(3, pg8::gemm_phase<CfgWp, EpiWp, pg8::ListOrder, true, true>(lds, (const char*)(a.ws + WS_WPOOL), (const char*)(a.ws + WS_WRAW), S, E); ); }
;         SUB(1, norm_rows(vcu * NWAVES + wave, lane, a.in[0], a.in[2], a.in[6], (const float*)(a.ws + WS_MOD), (f16*)(a.ws + WS_H)); );
;         SUB(2, if (vcu < 128) transpose_dispatch((320 + vcu) * 8 + wave, a.in[7], a.in[20], a.in[18], a.in[8], a.ws, scr, lane);
;                else { const int b2 = vcu - 128;
;                    for (int it = 448 + 3 * b2; it < 448 + 3 * b2 + 3; ++it) transpose_dispatch(it * 8 + wave, a.in[7], a.in[20], a.in[18], a.in[8], a.ws, scr, lane);
;                    if (b2 < 16) transpose_dispatch((832 + b2) * 8 + wave, a.in[7], a.in[20], a.in[18], a.in[8], a.ws, scr, lane); } );
;     );
.LBB0_230:
	s_cmp_eq_u32 s100, 1
	s_cbranch_scc0 .Lp1_seam
	s_mov_b32 s100, 2
	v_and_b32_e32 v22, 15, v0
	v_lshrrev_b32_e32 v1, 1, v0
	s_cmpk_gt_i32 s81, 0x7f
	s_cselect_b64 s[18:19], -1, 0
	s_branch .LBB0_165
